# k44 variant: PV V-fragment prefetch depth 2 instead of 4 (smaller LDS read burst when the PV segment starts)
# baseline (speedup 1.0000x reference)
; __device__ __forceinline__ void partialSM(f32x16& p0, f32x16& p1, float& m_reg, float& mn, float& alpha) {
;     ...
;   float mnC = -mn * C;
; #pragma unroll
;   for (int r = 0; r < 16; ++r) p0[r] = fmaf(p0[r], C, mnC);
; #pragma unroll
;   for (int r = 0; r < 16; ++r) p1[r] = fmaf(p1[r], C, mnC);
; #pragma unroll
;   for (int r = 0; r < 16; ++r) p0[r] = __builtin_amdgcn_exp2f(p0[r]);
; }
; __device__ __forceinline__ void finishSM(f32x16& p0, f32x16& p1, float alpha, float& l_reg, bf16x8& pa0, bf16x8& pa1, bf16x8& pa2, bf16x8& pa3) {
; #pragma unroll
;   for (int r = 0; r < 16; ++r) p1[r] = __builtin_amdgcn_exp2f(p1[r]);
;   float ps = 0;
; #pragma unroll
;   for (int r = 0; r < 16; ++r) ps += p0[r];
; #pragma unroll
;   for (int r = 0; r < 16; ++r) ps += p1[r];
;   { auto rr = __builtin_amdgcn_permlane32_swap(__float_as_uint(ps), __float_as_uint(ps), false, false);
;     ps = __uint_as_float(rr[0]) + __uint_as_float(rr[1]); }
;   l_reg = l_reg * alpha + ps;
;     ...
;   PK4(p0, 0, pa0); PK4(p0, 8, pa1); PK4(p1, 0, pa2); PK4(p1, 8, pa3);
;     ...
; }
; template <int I> __device__ __forceinline__ void pv_rd(int vb, s16x4& l, s16x4& h) {
;   constexpr int D0 = I >> 2, KS = I & 3, IMG = (D0 >> 2) * 16384, DD = D0 & 3;
;   l = tr_read<IMG + v_rd_off(DD, KS, 0)>(vb); h = tr_read<IMG + v_rd_off(DD, KS, 1)>(vb);
; }
; template <int I> __device__ __forceinline__ void pv_step(f32x16* o, int vb, const bf16x8 (&pa)[4], s16x4 (&l)[3], s16x4 (&h)[3]) {
;   if constexpr (I + 2 < 32) pv_rd<(I + 2 < 32 ? I + 2 : 0)>(vb, l[(I + 2) % 3], h[(I + 2) % 3]);
;   if constexpr (I + 2 < 32) asm volatile("s_waitcnt lgkmcnt(4)" ::: "memory"); else if constexpr (I + 1 < 32) asm volatile("s_waitcnt lgkmcnt(2)" ::: "memory"); else asm volatile("s_waitcnt lgkmcnt(0)" ::: "memory");
;   SBAR();
;   const s16x4 L = l[I % 3], H = h[I % 3];
;   o[I >> 2] = __builtin_amdgcn_mfma_f32_32x32x16_bf16(pa[I & 3], (bf16x8){L[0], L[1], L[2], L[3], H[0], H[1], H[2], H[3]}, o[I >> 2], 0, 0, 0);
;   SBAR();
;   if constexpr (I + 1 < 32) pv_step<(I + 1 < 32 ? I + 1 : 31)>(o, vb, pa, l, h);
; }
; __device__ __forceinline__ void pv_all_rolling(f32x16* o, int vb, bf16x8 pa0, bf16x8 pa1, bf16x8 pa2, bf16x8 pa3) {
;   const bf16x8 pa[4] = {pa0, pa1, pa2, pa3}; s16x4 l[3], h[3];
;   asm volatile("s_waitcnt lgkmcnt(0)" ::: "memory");
;   pv_rd<0>(vb, l[0], h[0]); pv_rd<1>(vb, l[1], h[1]);
;   pv_step<0>(o, vb, pa, l, h);
.LBB0_429:
	v_cndmask_b32_e64 v246, v223, v246, s[6:7]
	v_mul_f32_e32 v194, 0xbe0293ee, v246
	v_fmamk_f32 v146, v146, 0x3e0293ee, v194
	v_fmamk_f32 v147, v147, 0x3e0293ee, v194
	v_fmamk_f32 v148, v148, 0x3e0293ee, v194
	v_fmamk_f32 v149, v149, 0x3e0293ee, v194
	v_fmamk_f32 v150, v150, 0x3e0293ee, v194
	v_fmamk_f32 v151, v151, 0x3e0293ee, v194
	v_fmamk_f32 v152, v152, 0x3e0293ee, v194
	v_fmamk_f32 v153, v153, 0x3e0293ee, v194
	v_fmamk_f32 v154, v154, 0x3e0293ee, v194
	v_fmamk_f32 v155, v155, 0x3e0293ee, v194
	v_fmamk_f32 v156, v156, 0x3e0293ee, v194
	v_fmamk_f32 v157, v157, 0x3e0293ee, v194
	v_fmamk_f32 v158, v158, 0x3e0293ee, v194
	v_fmamk_f32 v159, v159, 0x3e0293ee, v194
	v_fmamk_f32 v160, v160, 0x3e0293ee, v194
	v_fmamk_f32 v161, v161, 0x3e0293ee, v194
	v_fmamk_f32 v130, v130, 0x3e0293ee, v194
	v_fmamk_f32 v131, v131, 0x3e0293ee, v194
	v_fmamk_f32 v132, v132, 0x3e0293ee, v194
	v_fmamk_f32 v133, v133, 0x3e0293ee, v194
	v_fmamk_f32 v134, v134, 0x3e0293ee, v194
	v_fmamk_f32 v135, v135, 0x3e0293ee, v194
	v_fmamk_f32 v136, v136, 0x3e0293ee, v194
	v_fmamk_f32 v137, v137, 0x3e0293ee, v194
	v_fmamk_f32 v138, v138, 0x3e0293ee, v194
	v_fmamk_f32 v139, v139, 0x3e0293ee, v194
	v_fmamk_f32 v140, v140, 0x3e0293ee, v194
	v_fmamk_f32 v141, v141, 0x3e0293ee, v194
	v_fmamk_f32 v142, v142, 0x3e0293ee, v194
	v_fmamk_f32 v143, v143, 0x3e0293ee, v194
	v_fmamk_f32 v144, v144, 0x3e0293ee, v194
	v_fmac_f32_e32 v194, 0x3e0293ee, v145
	v_exp_f32_e32 v145, v146
	v_exp_f32_e32 v146, v147
	v_exp_f32_e32 v147, v148
	v_exp_f32_e32 v148, v149
	v_exp_f32_e32 v149, v150
	v_exp_f32_e32 v150, v151
	v_exp_f32_e32 v151, v152
	v_exp_f32_e32 v152, v153
	v_exp_f32_e32 v153, v154
	v_exp_f32_e32 v154, v155
	v_exp_f32_e32 v155, v156
	v_exp_f32_e32 v156, v157
	v_exp_f32_e32 v157, v158
	v_exp_f32_e32 v158, v159
	v_exp_f32_e32 v159, v160
	v_exp_f32_e32 v160, v161
	v_add_f32_e32 v161, v247, v248
	v_fmac_f32_e32 v161, v245, v0
	v_exp_f32_e32 v0, v130
	v_add_f32_e32 v130, 0, v145
	v_add_f32_e32 v130, v146, v130
	v_add_f32_e32 v130, v147, v130
	v_add_f32_e32 v130, v148, v130
	v_add_f32_e32 v130, v149, v130
	s_waitcnt vmcnt(0)
	s_barrier
	s_setprio 0
	v_add_f32_e32 v130, v150, v130
	v_add_f32_e32 v130, v151, v130
	v_add_f32_e32 v130, v152, v130
	v_add_f32_e32 v130, v153, v130
	v_add_f32_e32 v130, v154, v130
	v_add_f32_e32 v130, v155, v130
	v_add_f32_e32 v130, v156, v130
	v_add_f32_e32 v130, v157, v130
	v_exp_f32_e32 v195, v131
	v_add_f32_e32 v130, v158, v130
	v_exp_f32_e32 v196, v132
	v_add_f32_e32 v130, v159, v130
	v_exp_f32_e32 v197, v133
	v_add_f32_e32 v130, v160, v130
	v_exp_f32_e32 v198, v134
	v_add_f32_e32 v130, v0, v130
	v_exp_f32_e32 v199, v135
	v_add_f32_e32 v130, v195, v130
	v_exp_f32_e32 v200, v136
	v_add_f32_e32 v130, v196, v130
	v_exp_f32_e32 v201, v137
	v_add_f32_e32 v130, v197, v130
	v_exp_f32_e32 v202, v138
	v_add_f32_e32 v130, v198, v130
	v_exp_f32_e32 v203, v139
	v_add_f32_e32 v130, v199, v130
	v_exp_f32_e32 v204, v140
	v_add_f32_e32 v130, v200, v130
	v_exp_f32_e32 v205, v141
	v_add_f32_e32 v130, v201, v130
	v_exp_f32_e32 v206, v142
	v_add_f32_e32 v130, v202, v130
	v_exp_f32_e32 v207, v143
	v_add_f32_e32 v130, v203, v130
	v_exp_f32_e32 v208, v144
	v_add_f32_e32 v130, v204, v130
	v_exp_f32_e32 v194, v194
	v_add_f32_e32 v130, v205, v130
	v_add_f32_e32 v130, v206, v130
	v_add_f32_e32 v130, v207, v130
	v_add_f32_e32 v130, v208, v130
	v_add_f32_e32 v130, v194, v130
	v_mov_b32_e32 v131, v130
	s_nop 1
	v_permlane32_swap_b32_e32 v130, v131
	v_add_f32_e32 v245, v130, v131
	v_fmac_f32_e32 v245, v161, v222
	v_cvt_pk_bf16_f32 v130, v145, v146
	v_cvt_pk_bf16_f32 v131, v147, v148
	v_cvt_pk_bf16_f32 v132, v149, v150
	v_cvt_pk_bf16_f32 v133, v151, v152
	v_cvt_pk_bf16_f32 v134, v153, v154
	v_cvt_pk_bf16_f32 v135, v155, v156
	v_cvt_pk_bf16_f32 v136, v157, v158
	v_cvt_pk_bf16_f32 v137, v159, v160
	v_cvt_pk_bf16_f32 v138, v0, v195
	v_cvt_pk_bf16_f32 v139, v196, v197
	v_cvt_pk_bf16_f32 v140, v198, v199
	v_cvt_pk_bf16_f32 v141, v200, v201
	v_cvt_pk_bf16_f32 v142, v202, v203
	v_cvt_pk_bf16_f32 v143, v204, v205
	v_cvt_pk_bf16_f32 v144, v206, v207
	v_cvt_pk_bf16_f32 v145, v208, v194
	s_nop 0
	v_permlane32_swap_b32_e32 v130, v132
	v_permlane32_swap_b32_e32 v131, v133
	v_permlane32_swap_b32_e32 v134, v136
	v_permlane32_swap_b32_e32 v135, v137
	v_permlane32_swap_b32_e32 v138, v140
	v_permlane32_swap_b32_e32 v139, v141
	v_permlane32_swap_b32_e32 v142, v144
	v_permlane32_swap_b32_e32 v143, v145
	s_waitcnt lgkmcnt(0)
	ds_read_b64_tr_b16 v[146:147], v244 offset:0
	ds_read_b64_tr_b16 v[148:149], v244 offset:2048
	ds_read_b64_tr_b16 v[150:151], v244 offset:4096
	ds_read_b64_tr_b16 v[152:153], v244 offset:6144
	ds_read_b64_tr_b16 v[154:155], v244 offset:8192
	ds_read_b64_tr_b16 v[156:157], v244 offset:10240
	v_lshl_add_u64 v[232:233], v[218:219], 0, s[22:23]
	v_lshl_add_u64 v[232:233], v[232:233], 0, s[14:15]
	s_mov_b32 m0, s29
	s_nop 0
	global_load_lds_dwordx4 v[232:233], off
	s_waitcnt lgkmcnt(4)
	s_nop 0
	v_mfma_f32_32x32x16_bf16 v[114:129], v[130:133], v[146:149], v[114:129]
	ds_read_b64_tr_b16 v[158:159], v244 offset:12288
	ds_read_b64_tr_b16 v[160:161], v244 offset:14336
	v_lshl_add_u64 v[232:233], v[218:219], 0, s[22:23]
	v_lshl_add_u64 v[232:233], v[232:233], 0, s[16:17]
	s_mov_b32 m0, s65
	s_nop 0
	global_load_lds_dwordx4 v[232:233], off
	s_waitcnt lgkmcnt(4)
	v_mfma_f32_32x32x16_bf16 v[114:129], v[134:137], v[150:153], v[114:129]
	ds_read_b64_tr_b16 v[194:195], v244 offset:512
	ds_read_b64_tr_b16 v[196:197], v244 offset:2560
	v_lshl_add_u64 v[232:233], v[220:221], 0, s[22:23]
	v_lshl_add_u64 v[232:233], v[232:233], 0, s[14:15]
	s_mov_b32 m0, s68
	s_nop 0
	global_load_lds_dwordx4 v[232:233], off
	s_waitcnt lgkmcnt(4)
; #define SBAR() __builtin_amdgcn_sched_barrier(0)
; #define DPUB() do { asm volatile("s_waitcnt vmcnt(0)" ::: "memory"); __syncthreads(); } while (0)
; #define DTILE(b) do { f32x16 p0 = f32x16{}, p1 = f32x16{}; float mn, al; bf16x8 pa0, pa1, pa2, pa3; \
;     qkt_rolling<(b) * DA_KB>(p0, p1, ka0, qr); partialSM(p0, p1, m_reg, mn, al); DRESC(al); finishSM(p0, p1, al, l_reg, pa0, pa1, pa2, pa3); SBAR(); \
;     pv_all_rolling(o, vb0 + (b) * DA_VB, pa0, pa1, pa2, pa3); } while (0)
; template <int I> __device__ __forceinline__ void pv_step(f32x16* o, int vb, const bf16x8 (&pa)[4], s16x4 (&l)[3], s16x4 (&h)[3]) {
;   if constexpr (I + 2 < 32) pv_rd<(I + 2 < 32 ? I + 2 : 0)>(vb, l[(I + 2) % 3], h[(I + 2) % 3]);
;   if constexpr (I + 2 < 32) asm volatile("s_waitcnt lgkmcnt(4)" ::: "memory"); else if constexpr (I + 1 < 32) asm volatile("s_waitcnt lgkmcnt(2)" ::: "memory"); else asm volatile("s_waitcnt lgkmcnt(0)" ::: "memory");
;   SBAR();
;   const s16x4 L = l[I % 3], H = h[I % 3];
;   o[I >> 2] = __builtin_amdgcn_mfma_f32_32x32x16_bf16(pa[I & 3], (bf16x8){L[0], L[1], L[2], L[3], H[0], H[1], H[2], H[3]}, o[I >> 2], 0, 0, 0);
;   SBAR();
;   if constexpr (I + 1 < 32) pv_step<(I + 1 < 32 ? I + 1 : 31)>(o, vb, pa, l, h);
; }
; __device__ __forceinline__ void pv_all_rolling(f32x16* o, int vb, bf16x8 pa0, bf16x8 pa1, bf16x8 pa2, bf16x8 pa3) {
;   const bf16x8 pa[4] = {pa0, pa1, pa2, pa3}; s16x4 l[3], h[3];
;   asm volatile("s_waitcnt lgkmcnt(0)" ::: "memory");
;   pv_rd<0>(vb, l[0], h[0]); pv_rd<1>(vb, l[1], h[1]);
;   pv_step<0>(o, vb, pa, l, h);
; __device__ __forceinline__ void unit_body_da(const Unit& U, char* lds) {
;     ...
;   for (int j = 0; j < NT; j += 2) {
;     DDMA(j + 1, 1); SBAR();
;     DTILE(0); SBAR(); DPUB();
;     if (j + 2 < NT) DDMA(j + 2, 0); SBAR();
;     DTILE(1); SBAR(); DPUB();
	v_mfma_f32_32x32x16_bf16 v[114:129], v[138:141], v[154:157], v[114:129]
	ds_read_b64_tr_b16 v[198:199], v244 offset:4608
	ds_read_b64_tr_b16 v[200:201], v244 offset:6656
	v_lshl_add_u64 v[232:233], v[220:221], 0, s[22:23]
	v_lshl_add_u64 v[232:233], v[232:233], 0, s[16:17]
	s_mov_b32 m0, s69
	s_nop 0
	global_load_lds_dwordx4 v[232:233], off
	s_waitcnt lgkmcnt(4)
	v_mfma_f32_32x32x16_bf16 v[114:129], v[142:145], v[158:161], v[114:129]
	ds_read_b64_tr_b16 v[202:203], v244 offset:8704
	ds_read_b64_tr_b16 v[204:205], v244 offset:10752
	s_waitcnt lgkmcnt(4)
	v_mfma_f32_32x32x16_bf16 v[98:113], v[130:133], v[194:197], v[98:113]
	ds_read_b64_tr_b16 v[206:207], v244 offset:12800
	ds_read_b64_tr_b16 v[208:209], v244 offset:14848
	s_waitcnt lgkmcnt(4)
	v_mfma_f32_32x32x16_bf16 v[98:113], v[134:137], v[198:201], v[98:113]
	ds_read_b64_tr_b16 v[146:147], v244 offset:1024
	ds_read_b64_tr_b16 v[148:149], v244 offset:3072
	s_waitcnt lgkmcnt(4)
	v_mfma_f32_32x32x16_bf16 v[98:113], v[138:141], v[202:205], v[98:113]
	ds_read_b64_tr_b16 v[150:151], v244 offset:5120
	ds_read_b64_tr_b16 v[152:153], v244 offset:7168
	s_waitcnt lgkmcnt(4)
	v_mfma_f32_32x32x16_bf16 v[98:113], v[142:145], v[206:209], v[98:113]
	ds_read_b64_tr_b16 v[154:155], v244 offset:9216
	ds_read_b64_tr_b16 v[156:157], v244 offset:11264
	s_waitcnt lgkmcnt(4)
	v_mfma_f32_32x32x16_bf16 v[82:97], v[130:133], v[146:149], v[82:97]
	ds_read_b64_tr_b16 v[158:159], v244 offset:13312
	ds_read_b64_tr_b16 v[160:161], v244 offset:15360
	s_waitcnt lgkmcnt(4)
	v_mfma_f32_32x32x16_bf16 v[82:97], v[134:137], v[150:153], v[82:97]
	ds_read_b64_tr_b16 v[194:195], v244 offset:1536
	ds_read_b64_tr_b16 v[196:197], v244 offset:3584
	s_waitcnt lgkmcnt(4)
	v_mfma_f32_32x32x16_bf16 v[82:97], v[138:141], v[154:157], v[82:97]
	ds_read_b64_tr_b16 v[198:199], v244 offset:5632
	ds_read_b64_tr_b16 v[200:201], v244 offset:7680
	s_waitcnt lgkmcnt(4)
	v_mfma_f32_32x32x16_bf16 v[82:97], v[142:145], v[158:161], v[82:97]
	ds_read_b64_tr_b16 v[202:203], v244 offset:9728
	ds_read_b64_tr_b16 v[204:205], v244 offset:11776
	s_waitcnt lgkmcnt(4)
	v_mfma_f32_32x32x16_bf16 v[66:81], v[130:133], v[194:197], v[66:81]
	ds_read_b64_tr_b16 v[206:207], v244 offset:13824
	ds_read_b64_tr_b16 v[208:209], v244 offset:15872
	s_waitcnt lgkmcnt(4)
	v_mfma_f32_32x32x16_bf16 v[66:81], v[134:137], v[198:201], v[66:81]
	ds_read_b64_tr_b16 v[146:147], v244 offset:16384
	ds_read_b64_tr_b16 v[148:149], v244 offset:18432
	s_waitcnt lgkmcnt(4)
	v_mfma_f32_32x32x16_bf16 v[66:81], v[138:141], v[202:205], v[66:81]
	ds_read_b64_tr_b16 v[150:151], v244 offset:20480
	ds_read_b64_tr_b16 v[152:153], v244 offset:22528
	s_waitcnt lgkmcnt(4)
	v_mfma_f32_32x32x16_bf16 v[66:81], v[142:145], v[206:209], v[66:81]
	ds_read_b64_tr_b16 v[154:155], v244 offset:24576
	ds_read_b64_tr_b16 v[156:157], v244 offset:26624
	s_waitcnt lgkmcnt(4)
	v_mfma_f32_32x32x16_bf16 v[50:65], v[130:133], v[146:149], v[50:65]
	ds_read_b64_tr_b16 v[158:159], v244 offset:28672
	ds_read_b64_tr_b16 v[160:161], v244 offset:30720
	s_waitcnt lgkmcnt(4)
	v_mfma_f32_32x32x16_bf16 v[50:65], v[134:137], v[150:153], v[50:65]
	ds_read_b64_tr_b16 v[194:195], v244 offset:16896
	ds_read_b64_tr_b16 v[196:197], v244 offset:18944
	s_waitcnt lgkmcnt(4)
	v_mfma_f32_32x32x16_bf16 v[50:65], v[138:141], v[154:157], v[50:65]
	ds_read_b64_tr_b16 v[198:199], v244 offset:20992
	ds_read_b64_tr_b16 v[200:201], v244 offset:23040
	s_waitcnt lgkmcnt(4)
	v_mfma_f32_32x32x16_bf16 v[50:65], v[142:145], v[158:161], v[50:65]
	ds_read_b64_tr_b16 v[202:203], v244 offset:25088
	ds_read_b64_tr_b16 v[204:205], v244 offset:27136
	s_waitcnt lgkmcnt(4)
	v_mfma_f32_32x32x16_bf16 v[34:49], v[130:133], v[194:197], v[34:49]
	ds_read_b64_tr_b16 v[206:207], v244 offset:29184
	ds_read_b64_tr_b16 v[208:209], v244 offset:31232
	s_waitcnt lgkmcnt(4)
	v_mfma_f32_32x32x16_bf16 v[34:49], v[134:137], v[198:201], v[34:49]
	ds_read_b64_tr_b16 v[146:147], v244 offset:17408
	ds_read_b64_tr_b16 v[148:149], v244 offset:19456
	s_waitcnt lgkmcnt(4)
	v_mfma_f32_32x32x16_bf16 v[34:49], v[138:141], v[202:205], v[34:49]
	ds_read_b64_tr_b16 v[150:151], v244 offset:21504
	ds_read_b64_tr_b16 v[152:153], v244 offset:23552
	s_waitcnt lgkmcnt(4)
	v_mfma_f32_32x32x16_bf16 v[34:49], v[142:145], v[206:209], v[34:49]
	ds_read_b64_tr_b16 v[154:155], v244 offset:25600
	ds_read_b64_tr_b16 v[156:157], v244 offset:27648
	s_waitcnt lgkmcnt(4)
	v_mfma_f32_32x32x16_bf16 v[18:33], v[130:133], v[146:149], v[18:33]
	ds_read_b64_tr_b16 v[158:159], v244 offset:29696
	ds_read_b64_tr_b16 v[160:161], v244 offset:31744
	s_waitcnt lgkmcnt(4)
	v_mfma_f32_32x32x16_bf16 v[18:33], v[134:137], v[150:153], v[18:33]
	ds_read_b64_tr_b16 v[194:195], v244 offset:17920
	ds_read_b64_tr_b16 v[196:197], v244 offset:19968
	s_waitcnt lgkmcnt(4)
	v_mfma_f32_32x32x16_bf16 v[18:33], v[138:141], v[154:157], v[18:33]
	ds_read_b64_tr_b16 v[198:199], v244 offset:22016
	ds_read_b64_tr_b16 v[200:201], v244 offset:24064
	s_waitcnt lgkmcnt(4)
	v_mfma_f32_32x32x16_bf16 v[18:33], v[142:145], v[158:161], v[18:33]
	ds_read_b64_tr_b16 v[202:203], v244 offset:26112
	ds_read_b64_tr_b16 v[204:205], v244 offset:28160
	s_waitcnt lgkmcnt(4)
	v_mfma_f32_32x32x16_bf16 v[2:17], v[130:133], v[194:197], v[2:17]
	ds_read_b64_tr_b16 v[206:207], v244 offset:30208
	ds_read_b64_tr_b16 v[208:209], v244 offset:32256
	s_waitcnt lgkmcnt(4)
	v_mfma_f32_32x32x16_bf16 v[2:17], v[134:137], v[198:201], v[2:17]
	s_waitcnt lgkmcnt(2)
	v_mfma_f32_32x32x16_bf16 v[2:17], v[138:141], v[202:205], v[2:17]
	s_waitcnt lgkmcnt(0)
	v_mfma_f32_32x32x16_bf16 v[2:17], v[142:145], v[206:209], v[2:17]
	s_waitcnt vmcnt(0)
	s_add_u32 s22, s22, 0x180000
	s_addc_u32 s23, s23, 0
	s_add_i32 s80, s80, 2
	s_and_b64 vcc, exec, s[46:47]
	s_waitcnt vmcnt(0) lgkmcnt(0)
	s_barrier
	s_cbranch_vccnz .LBB0_439

; __device__ __forceinline__ void partialSM(f32x16& p0, f32x16& p1, float& m_reg, float& mn, float& alpha) {
;     ...
;   float mnC = -mn * C;
; #pragma unroll
;   for (int r = 0; r < 16; ++r) p0[r] = fmaf(p0[r], C, mnC);
; #pragma unroll
;   for (int r = 0; r < 16; ++r) p1[r] = fmaf(p1[r], C, mnC);
; #pragma unroll
;   for (int r = 0; r < 16; ++r) p0[r] = __builtin_amdgcn_exp2f(p0[r]);
; }
; __device__ __forceinline__ void finishSM(f32x16& p0, f32x16& p1, float alpha, float& l_reg, bf16x8& pa0, bf16x8& pa1, bf16x8& pa2, bf16x8& pa3) {
; #pragma unroll
;   for (int r = 0; r < 16; ++r) p1[r] = __builtin_amdgcn_exp2f(p1[r]);
;   float ps = 0;
; #pragma unroll
;   for (int r = 0; r < 16; ++r) ps += p0[r];
; #pragma unroll
;   for (int r = 0; r < 16; ++r) ps += p1[r];
;   { auto rr = __builtin_amdgcn_permlane32_swap(__float_as_uint(ps), __float_as_uint(ps), false, false);
;     ps = __uint_as_float(rr[0]) + __uint_as_float(rr[1]); }
;   l_reg = l_reg * alpha + ps;
;     ...
;   PK4(p0, 0, pa0); PK4(p0, 8, pa1); PK4(p1, 0, pa2); PK4(p1, 8, pa3);
;     ...
; }
; __device__ __forceinline__ void pv_all_rolling(f32x16* o, int vb, bf16x8 pa0, bf16x8 pa1, bf16x8 pa2, bf16x8 pa3) {
;   const bf16x8 pa[4] = {pa0, pa1, pa2, pa3}; s16x4 l[3], h[3];
;   asm volatile("s_waitcnt lgkmcnt(0)" ::: "memory");
;   pv_rd<0>(vb, l[0], h[0]); pv_rd<1>(vb, l[1], h[1]);
;   pv_step<0>(o, vb, pa, l, h);
.LBB0_434:
	v_cndmask_b32_e64 v246, v247, v246, s[6:7]
	v_mul_f32_e32 v194, 0xbe0293ee, v246
	v_fmamk_f32 v146, v146, 0x3e0293ee, v194
	v_fmamk_f32 v147, v147, 0x3e0293ee, v194
	v_fmamk_f32 v148, v148, 0x3e0293ee, v194
	v_fmamk_f32 v149, v149, 0x3e0293ee, v194
	v_fmamk_f32 v150, v150, 0x3e0293ee, v194
	v_fmamk_f32 v151, v151, 0x3e0293ee, v194
	v_fmamk_f32 v152, v152, 0x3e0293ee, v194
	v_fmamk_f32 v153, v153, 0x3e0293ee, v194
	v_fmamk_f32 v154, v154, 0x3e0293ee, v194
	v_fmamk_f32 v155, v155, 0x3e0293ee, v194
	v_fmamk_f32 v156, v156, 0x3e0293ee, v194
	v_fmamk_f32 v157, v157, 0x3e0293ee, v194
	v_fmamk_f32 v158, v158, 0x3e0293ee, v194
	v_fmamk_f32 v159, v159, 0x3e0293ee, v194
	v_fmamk_f32 v160, v160, 0x3e0293ee, v194
	v_fmamk_f32 v161, v161, 0x3e0293ee, v194
	v_fmamk_f32 v130, v130, 0x3e0293ee, v194
	v_fmamk_f32 v131, v131, 0x3e0293ee, v194
	v_fmamk_f32 v132, v132, 0x3e0293ee, v194
	v_fmamk_f32 v133, v133, 0x3e0293ee, v194
	v_fmamk_f32 v134, v134, 0x3e0293ee, v194
	v_fmamk_f32 v135, v135, 0x3e0293ee, v194
	v_fmamk_f32 v136, v136, 0x3e0293ee, v194
	v_fmamk_f32 v137, v137, 0x3e0293ee, v194
	v_fmamk_f32 v138, v138, 0x3e0293ee, v194
	v_fmamk_f32 v139, v139, 0x3e0293ee, v194
	v_fmamk_f32 v140, v140, 0x3e0293ee, v194
	v_fmamk_f32 v141, v141, 0x3e0293ee, v194
	v_fmamk_f32 v142, v142, 0x3e0293ee, v194
	v_fmamk_f32 v143, v143, 0x3e0293ee, v194
	v_fmamk_f32 v144, v144, 0x3e0293ee, v194
	v_fmac_f32_e32 v194, 0x3e0293ee, v145
	v_exp_f32_e32 v145, v146
	v_exp_f32_e32 v146, v147
	v_exp_f32_e32 v147, v148
	v_exp_f32_e32 v148, v149
	v_exp_f32_e32 v149, v150
	v_exp_f32_e32 v150, v151
	v_exp_f32_e32 v151, v152
	v_exp_f32_e32 v152, v153
	v_exp_f32_e32 v153, v154
	v_exp_f32_e32 v154, v155
	v_exp_f32_e32 v155, v156
	v_exp_f32_e32 v156, v157
	v_exp_f32_e32 v157, v158
	v_exp_f32_e32 v158, v159
	v_exp_f32_e32 v159, v160
	v_exp_f32_e32 v160, v161
	v_exp_f32_e32 v161, v130
	v_add_f32_e32 v130, 0, v145
	v_add_f32_e32 v130, v146, v130
	v_add_f32_e32 v130, v147, v130
	v_add_f32_e32 v130, v148, v130
	v_add_f32_e32 v130, v149, v130
	v_add_f32_e32 v130, v150, v130
	v_add_f32_e32 v130, v151, v130
	s_waitcnt vmcnt(0)
	s_barrier
	s_setprio 0
	v_add_f32_e32 v130, v152, v130
	v_add_f32_e32 v130, v153, v130
	v_add_f32_e32 v130, v154, v130
	v_add_f32_e32 v130, v155, v130
	v_add_f32_e32 v130, v156, v130
	v_add_f32_e32 v130, v157, v130
	v_exp_f32_e32 v195, v131
	v_add_f32_e32 v130, v158, v130
	v_exp_f32_e32 v196, v132
	v_add_f32_e32 v130, v159, v130
	v_exp_f32_e32 v197, v133
	v_add_f32_e32 v130, v160, v130
	v_exp_f32_e32 v198, v134
	v_add_f32_e32 v130, v161, v130
	v_exp_f32_e32 v199, v135
	v_add_f32_e32 v130, v195, v130
	v_exp_f32_e32 v200, v136
	v_add_f32_e32 v130, v196, v130
	v_exp_f32_e32 v201, v137
	v_add_f32_e32 v130, v197, v130
	v_exp_f32_e32 v202, v138
	v_add_f32_e32 v130, v198, v130
	v_exp_f32_e32 v203, v139
	v_add_f32_e32 v130, v199, v130
	v_exp_f32_e32 v204, v140
	v_add_f32_e32 v130, v200, v130
	v_exp_f32_e32 v205, v141
	v_add_f32_e32 v130, v201, v130
	v_exp_f32_e32 v206, v142
	v_add_f32_e32 v130, v202, v130
	v_exp_f32_e32 v207, v143
	v_add_f32_e32 v130, v203, v130
	v_exp_f32_e32 v208, v144
	v_add_f32_e32 v130, v204, v130
	v_exp_f32_e32 v194, v194
	v_add_f32_e32 v130, v205, v130
	v_add_f32_e32 v130, v206, v130
	v_add_f32_e32 v130, v207, v130
	v_add_f32_e32 v130, v208, v130
	v_add_f32_e32 v247, v194, v130
	v_mov_b32_e32 v248, v247
	s_nop 1
	v_permlane32_swap_b32_e32 v247, v248
	v_cvt_pk_bf16_f32 v130, v145, v146
	v_cvt_pk_bf16_f32 v131, v147, v148
	v_cvt_pk_bf16_f32 v132, v149, v150
	v_cvt_pk_bf16_f32 v133, v151, v152
	v_cvt_pk_bf16_f32 v134, v153, v154
	v_cvt_pk_bf16_f32 v135, v155, v156
	v_cvt_pk_bf16_f32 v136, v157, v158
	v_cvt_pk_bf16_f32 v137, v159, v160
	v_cvt_pk_bf16_f32 v138, v161, v195
	v_cvt_pk_bf16_f32 v139, v196, v197
	v_cvt_pk_bf16_f32 v140, v198, v199
	v_cvt_pk_bf16_f32 v141, v200, v201
	v_cvt_pk_bf16_f32 v142, v202, v203
	v_cvt_pk_bf16_f32 v143, v204, v205
	v_cvt_pk_bf16_f32 v144, v206, v207
	v_cvt_pk_bf16_f32 v145, v208, v194
	s_nop 0
	v_permlane32_swap_b32_e32 v130, v132
	v_permlane32_swap_b32_e32 v131, v133
	v_permlane32_swap_b32_e32 v134, v136
	v_permlane32_swap_b32_e32 v135, v137
	v_permlane32_swap_b32_e32 v138, v140
	v_permlane32_swap_b32_e32 v139, v141
	v_permlane32_swap_b32_e32 v142, v144
	v_permlane32_swap_b32_e32 v143, v145
	s_waitcnt lgkmcnt(0)
	ds_read_b64_tr_b16 v[146:147], v213 offset:0
	ds_read_b64_tr_b16 v[148:149], v213 offset:2048
	ds_read_b64_tr_b16 v[150:151], v213 offset:4096
	ds_read_b64_tr_b16 v[152:153], v213 offset:6144
	ds_read_b64_tr_b16 v[154:155], v213 offset:8192
	ds_read_b64_tr_b16 v[156:157], v213 offset:10240
	v_lshl_add_u64 v[232:233], v[218:219], 0, s[22:23]
	v_lshl_add_u64 v[232:233], v[232:233], 0, s[10:11]
	s_add_i32 m0, s29, 0x8000
	s_nop 0
	global_load_lds_dwordx4 v[232:233], off
	s_waitcnt lgkmcnt(4)
	s_nop 0
	v_mfma_f32_32x32x16_bf16 v[114:129], v[130:133], v[146:149], v[114:129]
	ds_read_b64_tr_b16 v[158:159], v213 offset:12288
	ds_read_b64_tr_b16 v[160:161], v213 offset:14336
	v_lshl_add_u64 v[232:233], v[218:219], 0, s[22:23]
	v_lshl_add_u64 v[232:233], v[232:233], 0, s[12:13]
	s_add_i32 m0, s29, 0xc000
	s_nop 0
	global_load_lds_dwordx4 v[232:233], off
	s_waitcnt lgkmcnt(4)
	v_mfma_f32_32x32x16_bf16 v[114:129], v[134:137], v[150:153], v[114:129]
	ds_read_b64_tr_b16 v[194:195], v213 offset:512
	ds_read_b64_tr_b16 v[196:197], v213 offset:2560
	v_lshl_add_u64 v[232:233], v[220:221], 0, s[22:23]
	v_lshl_add_u64 v[232:233], v[232:233], 0, s[10:11]
	s_add_i32 m0, s29, 0x8400
	s_nop 0
	global_load_lds_dwordx4 v[232:233], off
	s_waitcnt lgkmcnt(4)
; #define SBAR() __builtin_amdgcn_sched_barrier(0)
; #define DPUB() do { asm volatile("s_waitcnt vmcnt(0)" ::: "memory"); __syncthreads(); } while (0)
; #define DTILE(b) do { f32x16 p0 = f32x16{}, p1 = f32x16{}; float mn, al; bf16x8 pa0, pa1, pa2, pa3; \
;     qkt_rolling<(b) * DA_KB>(p0, p1, ka0, qr); partialSM(p0, p1, m_reg, mn, al); DRESC(al); finishSM(p0, p1, al, l_reg, pa0, pa1, pa2, pa3); SBAR(); \
;     pv_all_rolling(o, vb0 + (b) * DA_VB, pa0, pa1, pa2, pa3); } while (0)
; template <int I> __device__ __forceinline__ void pv_step(f32x16* o, int vb, const bf16x8 (&pa)[4], s16x4 (&l)[3], s16x4 (&h)[3]) {
;   if constexpr (I + 2 < 32) pv_rd<(I + 2 < 32 ? I + 2 : 0)>(vb, l[(I + 2) % 3], h[(I + 2) % 3]);
;   if constexpr (I + 2 < 32) asm volatile("s_waitcnt lgkmcnt(4)" ::: "memory"); else if constexpr (I + 1 < 32) asm volatile("s_waitcnt lgkmcnt(2)" ::: "memory"); else asm volatile("s_waitcnt lgkmcnt(0)" ::: "memory");
;   SBAR();
;   const s16x4 L = l[I % 3], H = h[I % 3];
;   o[I >> 2] = __builtin_amdgcn_mfma_f32_32x32x16_bf16(pa[I & 3], (bf16x8){L[0], L[1], L[2], L[3], H[0], H[1], H[2], H[3]}, o[I >> 2], 0, 0, 0);
;   SBAR();
;   if constexpr (I + 1 < 32) pv_step<(I + 1 < 32 ? I + 1 : 31)>(o, vb, pa, l, h);
; }
; __device__ __forceinline__ void unit_body_da(const Unit& U, char* lds) {
;     ...
;   for (int j = 0; j < NT; j += 2) {
;     DDMA(j + 1, 1); SBAR();
;     DTILE(0); SBAR(); DPUB();
;     if (j + 2 < NT) DDMA(j + 2, 0); SBAR();
;     DTILE(1); SBAR(); DPUB();
	v_mfma_f32_32x32x16_bf16 v[114:129], v[138:141], v[154:157], v[114:129]
	ds_read_b64_tr_b16 v[198:199], v213 offset:4608
	ds_read_b64_tr_b16 v[200:201], v213 offset:6656
	v_lshl_add_u64 v[232:233], v[220:221], 0, s[22:23]
	v_lshl_add_u64 v[232:233], v[232:233], 0, s[12:13]
	s_add_i32 m0, s29, 0xc400
	s_nop 0
	global_load_lds_dwordx4 v[232:233], off
	s_waitcnt lgkmcnt(4)
	v_mfma_f32_32x32x16_bf16 v[114:129], v[142:145], v[158:161], v[114:129]
	ds_read_b64_tr_b16 v[202:203], v213 offset:8704
	ds_read_b64_tr_b16 v[204:205], v213 offset:10752
	s_waitcnt lgkmcnt(4)
	v_mfma_f32_32x32x16_bf16 v[98:113], v[130:133], v[194:197], v[98:113]
	ds_read_b64_tr_b16 v[206:207], v213 offset:12800
	ds_read_b64_tr_b16 v[208:209], v213 offset:14848
	s_waitcnt lgkmcnt(4)
	v_mfma_f32_32x32x16_bf16 v[98:113], v[134:137], v[198:201], v[98:113]
	ds_read_b64_tr_b16 v[146:147], v213 offset:1024
	ds_read_b64_tr_b16 v[148:149], v213 offset:3072
	s_waitcnt lgkmcnt(4)
	v_mfma_f32_32x32x16_bf16 v[98:113], v[138:141], v[202:205], v[98:113]
	ds_read_b64_tr_b16 v[150:151], v213 offset:5120
	ds_read_b64_tr_b16 v[152:153], v213 offset:7168
	s_waitcnt lgkmcnt(4)
	v_mfma_f32_32x32x16_bf16 v[98:113], v[142:145], v[206:209], v[98:113]
	ds_read_b64_tr_b16 v[154:155], v213 offset:9216
	ds_read_b64_tr_b16 v[156:157], v213 offset:11264
	s_waitcnt lgkmcnt(4)
	v_mfma_f32_32x32x16_bf16 v[82:97], v[130:133], v[146:149], v[82:97]
	ds_read_b64_tr_b16 v[158:159], v213 offset:13312
	ds_read_b64_tr_b16 v[160:161], v213 offset:15360
	s_waitcnt lgkmcnt(4)
	v_mfma_f32_32x32x16_bf16 v[82:97], v[134:137], v[150:153], v[82:97]
	ds_read_b64_tr_b16 v[194:195], v213 offset:1536
	ds_read_b64_tr_b16 v[196:197], v213 offset:3584
	s_waitcnt lgkmcnt(4)
	v_mfma_f32_32x32x16_bf16 v[82:97], v[138:141], v[154:157], v[82:97]
	ds_read_b64_tr_b16 v[198:199], v213 offset:5632
	ds_read_b64_tr_b16 v[200:201], v213 offset:7680
	s_waitcnt lgkmcnt(4)
	v_mfma_f32_32x32x16_bf16 v[82:97], v[142:145], v[158:161], v[82:97]
	ds_read_b64_tr_b16 v[202:203], v213 offset:9728
	ds_read_b64_tr_b16 v[204:205], v213 offset:11776
	s_waitcnt lgkmcnt(4)
	v_mfma_f32_32x32x16_bf16 v[66:81], v[130:133], v[194:197], v[66:81]
	ds_read_b64_tr_b16 v[206:207], v213 offset:13824
	ds_read_b64_tr_b16 v[208:209], v213 offset:15872
	s_waitcnt lgkmcnt(4)
	v_mfma_f32_32x32x16_bf16 v[66:81], v[134:137], v[198:201], v[66:81]
	ds_read_b64_tr_b16 v[146:147], v213 offset:16384
	ds_read_b64_tr_b16 v[148:149], v213 offset:18432
	s_waitcnt lgkmcnt(4)
	v_mfma_f32_32x32x16_bf16 v[66:81], v[138:141], v[202:205], v[66:81]
	ds_read_b64_tr_b16 v[150:151], v213 offset:20480
	ds_read_b64_tr_b16 v[152:153], v213 offset:22528
	s_waitcnt lgkmcnt(4)
	v_mfma_f32_32x32x16_bf16 v[66:81], v[142:145], v[206:209], v[66:81]
	ds_read_b64_tr_b16 v[154:155], v213 offset:24576
	ds_read_b64_tr_b16 v[156:157], v213 offset:26624
	s_waitcnt lgkmcnt(4)
	v_mfma_f32_32x32x16_bf16 v[50:65], v[130:133], v[146:149], v[50:65]
	ds_read_b64_tr_b16 v[158:159], v213 offset:28672
	ds_read_b64_tr_b16 v[160:161], v213 offset:30720
	s_waitcnt lgkmcnt(4)
	v_mfma_f32_32x32x16_bf16 v[50:65], v[134:137], v[150:153], v[50:65]
	ds_read_b64_tr_b16 v[194:195], v213 offset:16896
	ds_read_b64_tr_b16 v[196:197], v213 offset:18944
	s_waitcnt lgkmcnt(4)
	v_mfma_f32_32x32x16_bf16 v[50:65], v[138:141], v[154:157], v[50:65]
	ds_read_b64_tr_b16 v[198:199], v213 offset:20992
	ds_read_b64_tr_b16 v[200:201], v213 offset:23040
	s_waitcnt lgkmcnt(4)
	v_mfma_f32_32x32x16_bf16 v[50:65], v[142:145], v[158:161], v[50:65]
	ds_read_b64_tr_b16 v[202:203], v213 offset:25088
	ds_read_b64_tr_b16 v[204:205], v213 offset:27136
	s_waitcnt lgkmcnt(4)
	v_mfma_f32_32x32x16_bf16 v[34:49], v[130:133], v[194:197], v[34:49]
	ds_read_b64_tr_b16 v[206:207], v213 offset:29184
	ds_read_b64_tr_b16 v[208:209], v213 offset:31232
	s_waitcnt lgkmcnt(4)
	v_mfma_f32_32x32x16_bf16 v[34:49], v[134:137], v[198:201], v[34:49]
	ds_read_b64_tr_b16 v[146:147], v213 offset:17408
	ds_read_b64_tr_b16 v[148:149], v213 offset:19456
	s_waitcnt lgkmcnt(4)
	v_mfma_f32_32x32x16_bf16 v[34:49], v[138:141], v[202:205], v[34:49]
	ds_read_b64_tr_b16 v[150:151], v213 offset:21504
	ds_read_b64_tr_b16 v[152:153], v213 offset:23552
	s_waitcnt lgkmcnt(4)
	v_mfma_f32_32x32x16_bf16 v[34:49], v[142:145], v[206:209], v[34:49]
	ds_read_b64_tr_b16 v[154:155], v213 offset:25600
	ds_read_b64_tr_b16 v[156:157], v213 offset:27648
	s_waitcnt lgkmcnt(4)
	v_mfma_f32_32x32x16_bf16 v[18:33], v[130:133], v[146:149], v[18:33]
	ds_read_b64_tr_b16 v[158:159], v213 offset:29696
	ds_read_b64_tr_b16 v[160:161], v213 offset:31744
	s_waitcnt lgkmcnt(4)
	v_mfma_f32_32x32x16_bf16 v[18:33], v[134:137], v[150:153], v[18:33]
	ds_read_b64_tr_b16 v[194:195], v213 offset:17920
	ds_read_b64_tr_b16 v[196:197], v213 offset:19968
	s_waitcnt lgkmcnt(4)
	v_mfma_f32_32x32x16_bf16 v[18:33], v[138:141], v[154:157], v[18:33]
	ds_read_b64_tr_b16 v[198:199], v213 offset:22016
	ds_read_b64_tr_b16 v[200:201], v213 offset:24064
	s_waitcnt lgkmcnt(4)
	v_mfma_f32_32x32x16_bf16 v[18:33], v[142:145], v[158:161], v[18:33]
	ds_read_b64_tr_b16 v[202:203], v213 offset:26112
	ds_read_b64_tr_b16 v[204:205], v213 offset:28160
	s_waitcnt lgkmcnt(4)
	v_mfma_f32_32x32x16_bf16 v[2:17], v[130:133], v[194:197], v[2:17]
	ds_read_b64_tr_b16 v[206:207], v213 offset:30208
	ds_read_b64_tr_b16 v[208:209], v213 offset:32256
	s_waitcnt lgkmcnt(4)
	v_mfma_f32_32x32x16_bf16 v[2:17], v[134:137], v[198:201], v[2:17]
	s_waitcnt lgkmcnt(2)
	v_mfma_f32_32x32x16_bf16 v[2:17], v[138:141], v[202:205], v[2:17]
	s_waitcnt lgkmcnt(0)
	v_mfma_f32_32x32x16_bf16 v[2:17], v[142:145], v[206:209], v[2:17]
	s_waitcnt vmcnt(0)
	s_cmp_ge_u32 s80, s0
	s_cselect_b64 s[46:47], -1, 0
	s_and_b64 vcc, exec, s[46:47]
	s_waitcnt vmcnt(0) lgkmcnt(0)
	s_barrier

; __device__ __forceinline__ void partialSM(f32x16& p0, f32x16& p1, float& m_reg, float& mn, float& alpha) {
;     ...
;   float mnC = -mn * C;
; #pragma unroll
;   for (int r = 0; r < 16; ++r) p0[r] = fmaf(p0[r], C, mnC);
; #pragma unroll
;   for (int r = 0; r < 16; ++r) p1[r] = fmaf(p1[r], C, mnC);
; #pragma unroll
;   for (int r = 0; r < 16; ++r) p0[r] = __builtin_amdgcn_exp2f(p0[r]);
; }
; __device__ __forceinline__ void finishSM(f32x16& p0, f32x16& p1, float alpha, float& l_reg, bf16x8& pa0, bf16x8& pa1, bf16x8& pa2, bf16x8& pa3) {
; #pragma unroll
;   for (int r = 0; r < 16; ++r) p1[r] = __builtin_amdgcn_exp2f(p1[r]);
;   float ps = 0;
; #pragma unroll
;   for (int r = 0; r < 16; ++r) ps += p0[r];
; #pragma unroll
;   for (int r = 0; r < 16; ++r) ps += p1[r];
;   { auto rr = __builtin_amdgcn_permlane32_swap(__float_as_uint(ps), __float_as_uint(ps), false, false);
;     ps = __uint_as_float(rr[0]) + __uint_as_float(rr[1]); }
;   l_reg = l_reg * alpha + ps;
;     ...
;   PK4(p0, 0, pa0); PK4(p0, 8, pa1); PK4(p1, 0, pa2); PK4(p1, 8, pa3);
;     ...
; }
; __device__ __forceinline__ void pv_all_rolling(f32x16* o, int vb, bf16x8 pa0, bf16x8 pa1, bf16x8 pa2, bf16x8 pa3) {
;   const bf16x8 pa[4] = {pa0, pa1, pa2, pa3}; s16x4 l[3], h[3];
;   asm volatile("s_waitcnt lgkmcnt(0)" ::: "memory");
;   pv_rd<0>(vb, l[0], h[0]); pv_rd<1>(vb, l[1], h[1]);
;   pv_step<0>(o, vb, pa, l, h);
.LBB0_1435:
	v_cndmask_b32_e64 v246, v223, v246, s[6:7]
	v_mul_f32_e32 v194, 0xbe0293ee, v246
	v_fmamk_f32 v146, v146, 0x3e0293ee, v194
	v_fmamk_f32 v147, v147, 0x3e0293ee, v194
	v_fmamk_f32 v148, v148, 0x3e0293ee, v194
	v_fmamk_f32 v149, v149, 0x3e0293ee, v194
	v_fmamk_f32 v150, v150, 0x3e0293ee, v194
	v_fmamk_f32 v151, v151, 0x3e0293ee, v194
	v_fmamk_f32 v152, v152, 0x3e0293ee, v194
	v_fmamk_f32 v153, v153, 0x3e0293ee, v194
	v_fmamk_f32 v154, v154, 0x3e0293ee, v194
	v_fmamk_f32 v155, v155, 0x3e0293ee, v194
	v_fmamk_f32 v156, v156, 0x3e0293ee, v194
	v_fmamk_f32 v157, v157, 0x3e0293ee, v194
	v_fmamk_f32 v158, v158, 0x3e0293ee, v194
	v_fmamk_f32 v159, v159, 0x3e0293ee, v194
	v_fmamk_f32 v160, v160, 0x3e0293ee, v194
	v_fmamk_f32 v161, v161, 0x3e0293ee, v194
	v_fmamk_f32 v130, v130, 0x3e0293ee, v194
	v_fmamk_f32 v131, v131, 0x3e0293ee, v194
	v_fmamk_f32 v132, v132, 0x3e0293ee, v194
	v_fmamk_f32 v133, v133, 0x3e0293ee, v194
	v_fmamk_f32 v134, v134, 0x3e0293ee, v194
	v_fmamk_f32 v135, v135, 0x3e0293ee, v194
	v_fmamk_f32 v136, v136, 0x3e0293ee, v194
	v_fmamk_f32 v137, v137, 0x3e0293ee, v194
	v_fmamk_f32 v138, v138, 0x3e0293ee, v194
	v_fmamk_f32 v139, v139, 0x3e0293ee, v194
	v_fmamk_f32 v140, v140, 0x3e0293ee, v194
	v_fmamk_f32 v141, v141, 0x3e0293ee, v194
	v_fmamk_f32 v142, v142, 0x3e0293ee, v194
	v_fmamk_f32 v143, v143, 0x3e0293ee, v194
	v_fmamk_f32 v144, v144, 0x3e0293ee, v194
	v_fmac_f32_e32 v194, 0x3e0293ee, v145
	v_exp_f32_e32 v145, v146
	v_exp_f32_e32 v146, v147
	v_exp_f32_e32 v147, v148
	v_exp_f32_e32 v148, v149
	v_exp_f32_e32 v149, v150
	v_exp_f32_e32 v150, v151
	v_exp_f32_e32 v151, v152
	v_exp_f32_e32 v152, v153
	v_exp_f32_e32 v153, v154
	v_exp_f32_e32 v154, v155
	v_exp_f32_e32 v155, v156
	v_exp_f32_e32 v156, v157
	v_exp_f32_e32 v157, v158
	v_exp_f32_e32 v158, v159
	v_exp_f32_e32 v159, v160
	v_exp_f32_e32 v160, v161
	v_add_f32_e32 v161, v247, v248
	v_fmac_f32_e32 v161, v245, v0
	v_exp_f32_e32 v0, v130
	v_add_f32_e32 v130, 0, v145
	v_add_f32_e32 v130, v146, v130
	v_add_f32_e32 v130, v147, v130
	v_add_f32_e32 v130, v148, v130
	v_add_f32_e32 v130, v149, v130
	s_waitcnt vmcnt(0)
	s_barrier
	s_setprio 0
	v_add_f32_e32 v130, v150, v130
	v_add_f32_e32 v130, v151, v130
	v_add_f32_e32 v130, v152, v130
	v_add_f32_e32 v130, v153, v130
	v_add_f32_e32 v130, v154, v130
	v_add_f32_e32 v130, v155, v130
	v_add_f32_e32 v130, v156, v130
	v_add_f32_e32 v130, v157, v130
	v_exp_f32_e32 v195, v131
	v_add_f32_e32 v130, v158, v130
	v_exp_f32_e32 v196, v132
	v_add_f32_e32 v130, v159, v130
	v_exp_f32_e32 v197, v133
	v_add_f32_e32 v130, v160, v130
	v_exp_f32_e32 v198, v134
	v_add_f32_e32 v130, v0, v130
	v_exp_f32_e32 v199, v135
	v_add_f32_e32 v130, v195, v130
	v_exp_f32_e32 v200, v136
	v_add_f32_e32 v130, v196, v130
	v_exp_f32_e32 v201, v137
	v_add_f32_e32 v130, v197, v130
	v_exp_f32_e32 v202, v138
	v_add_f32_e32 v130, v198, v130
	v_exp_f32_e32 v203, v139
	v_add_f32_e32 v130, v199, v130
	v_exp_f32_e32 v204, v140
	v_add_f32_e32 v130, v200, v130
	v_exp_f32_e32 v205, v141
	v_add_f32_e32 v130, v201, v130
	v_exp_f32_e32 v206, v142
	v_add_f32_e32 v130, v202, v130
	v_exp_f32_e32 v207, v143
	v_add_f32_e32 v130, v203, v130
	v_exp_f32_e32 v208, v144
	v_add_f32_e32 v130, v204, v130
	v_exp_f32_e32 v194, v194
	v_add_f32_e32 v130, v205, v130
	v_add_f32_e32 v130, v206, v130
	v_add_f32_e32 v130, v207, v130
	v_add_f32_e32 v130, v208, v130
	v_add_f32_e32 v130, v194, v130
	v_mov_b32_e32 v131, v130
	s_nop 1
	v_permlane32_swap_b32_e32 v130, v131
	v_add_f32_e32 v245, v130, v131
	v_fmac_f32_e32 v245, v161, v222
	v_cvt_pk_bf16_f32 v130, v145, v146
	v_cvt_pk_bf16_f32 v131, v147, v148
	v_cvt_pk_bf16_f32 v132, v149, v150
	v_cvt_pk_bf16_f32 v133, v151, v152
	v_cvt_pk_bf16_f32 v134, v153, v154
	v_cvt_pk_bf16_f32 v135, v155, v156
	v_cvt_pk_bf16_f32 v136, v157, v158
	v_cvt_pk_bf16_f32 v137, v159, v160
	v_cvt_pk_bf16_f32 v138, v0, v195
	v_cvt_pk_bf16_f32 v139, v196, v197
	v_cvt_pk_bf16_f32 v140, v198, v199
	v_cvt_pk_bf16_f32 v141, v200, v201
	v_cvt_pk_bf16_f32 v142, v202, v203
	v_cvt_pk_bf16_f32 v143, v204, v205
	v_cvt_pk_bf16_f32 v144, v206, v207
	v_cvt_pk_bf16_f32 v145, v208, v194
	s_nop 0
	v_permlane32_swap_b32_e32 v130, v132
	v_permlane32_swap_b32_e32 v131, v133
	v_permlane32_swap_b32_e32 v134, v136
	v_permlane32_swap_b32_e32 v135, v137
	v_permlane32_swap_b32_e32 v138, v140
	v_permlane32_swap_b32_e32 v139, v141
	v_permlane32_swap_b32_e32 v142, v144
	v_permlane32_swap_b32_e32 v143, v145
	s_waitcnt lgkmcnt(0)
	ds_read_b64_tr_b16 v[146:147], v244 offset:0
	ds_read_b64_tr_b16 v[148:149], v244 offset:2048
	ds_read_b64_tr_b16 v[150:151], v244 offset:4096
	ds_read_b64_tr_b16 v[152:153], v244 offset:6144
	ds_read_b64_tr_b16 v[154:155], v244 offset:8192
	ds_read_b64_tr_b16 v[156:157], v244 offset:10240
	v_lshl_add_u64 v[232:233], v[218:219], 0, s[22:23]
	v_lshl_add_u64 v[232:233], v[232:233], 0, s[14:15]
	s_mov_b32 m0, s62
	s_nop 0
	global_load_lds_dwordx4 v[232:233], off
	s_waitcnt lgkmcnt(4)
	s_nop 0
	v_mfma_f32_32x32x16_bf16 v[114:129], v[130:133], v[146:149], v[114:129]
	ds_read_b64_tr_b16 v[158:159], v244 offset:12288
	ds_read_b64_tr_b16 v[160:161], v244 offset:14336
	v_lshl_add_u64 v[232:233], v[218:219], 0, s[22:23]
	v_lshl_add_u64 v[232:233], v[232:233], 0, s[16:17]
	s_mov_b32 m0, s63
	s_nop 0
	global_load_lds_dwordx4 v[232:233], off
	s_waitcnt lgkmcnt(4)
	v_mfma_f32_32x32x16_bf16 v[114:129], v[134:137], v[150:153], v[114:129]
	ds_read_b64_tr_b16 v[194:195], v244 offset:512
	ds_read_b64_tr_b16 v[196:197], v244 offset:2560
	v_lshl_add_u64 v[232:233], v[220:221], 0, s[22:23]
	v_lshl_add_u64 v[232:233], v[232:233], 0, s[14:15]
	s_mov_b32 m0, s68
	s_nop 0
	global_load_lds_dwordx4 v[232:233], off
	s_waitcnt lgkmcnt(4)
; #define SBAR() __builtin_amdgcn_sched_barrier(0)
; #define DPUB() do { asm volatile("s_waitcnt vmcnt(0)" ::: "memory"); __syncthreads(); } while (0)
; #define DTILE(b) do { f32x16 p0 = f32x16{}, p1 = f32x16{}; float mn, al; bf16x8 pa0, pa1, pa2, pa3; \
;     qkt_rolling<(b) * DA_KB>(p0, p1, ka0, qr); partialSM(p0, p1, m_reg, mn, al); DRESC(al); finishSM(p0, p1, al, l_reg, pa0, pa1, pa2, pa3); SBAR(); \
;     pv_all_rolling(o, vb0 + (b) * DA_VB, pa0, pa1, pa2, pa3); } while (0)
; template <int I> __device__ __forceinline__ void pv_step(f32x16* o, int vb, const bf16x8 (&pa)[4], s16x4 (&l)[3], s16x4 (&h)[3]) {
;   if constexpr (I + 2 < 32) pv_rd<(I + 2 < 32 ? I + 2 : 0)>(vb, l[(I + 2) % 3], h[(I + 2) % 3]);
;   if constexpr (I + 2 < 32) asm volatile("s_waitcnt lgkmcnt(4)" ::: "memory"); else if constexpr (I + 1 < 32) asm volatile("s_waitcnt lgkmcnt(2)" ::: "memory"); else asm volatile("s_waitcnt lgkmcnt(0)" ::: "memory");
;   SBAR();
;   const s16x4 L = l[I % 3], H = h[I % 3];
;   o[I >> 2] = __builtin_amdgcn_mfma_f32_32x32x16_bf16(pa[I & 3], (bf16x8){L[0], L[1], L[2], L[3], H[0], H[1], H[2], H[3]}, o[I >> 2], 0, 0, 0);
;   SBAR();
;   if constexpr (I + 1 < 32) pv_step<(I + 1 < 32 ? I + 1 : 31)>(o, vb, pa, l, h);
; }
; __device__ __forceinline__ void unit_body_da(const Unit& U, char* lds) {
;     ...
;   for (int j = 0; j < NT; j += 2) {
;     DDMA(j + 1, 1); SBAR();
;     DTILE(0); SBAR(); DPUB();
;     if (j + 2 < NT) DDMA(j + 2, 0); SBAR();
;     DTILE(1); SBAR(); DPUB();
	v_mfma_f32_32x32x16_bf16 v[114:129], v[138:141], v[154:157], v[114:129]
	ds_read_b64_tr_b16 v[198:199], v244 offset:4608
	ds_read_b64_tr_b16 v[200:201], v244 offset:6656
	v_lshl_add_u64 v[232:233], v[220:221], 0, s[22:23]
	v_lshl_add_u64 v[232:233], v[232:233], 0, s[16:17]
	s_mov_b32 m0, s69
	s_nop 0
	global_load_lds_dwordx4 v[232:233], off
	s_waitcnt lgkmcnt(4)
	v_mfma_f32_32x32x16_bf16 v[114:129], v[142:145], v[158:161], v[114:129]
	ds_read_b64_tr_b16 v[202:203], v244 offset:8704
	ds_read_b64_tr_b16 v[204:205], v244 offset:10752
	s_waitcnt lgkmcnt(4)
	v_mfma_f32_32x32x16_bf16 v[98:113], v[130:133], v[194:197], v[98:113]
	ds_read_b64_tr_b16 v[206:207], v244 offset:12800
	ds_read_b64_tr_b16 v[208:209], v244 offset:14848
	s_waitcnt lgkmcnt(4)
	v_mfma_f32_32x32x16_bf16 v[98:113], v[134:137], v[198:201], v[98:113]
	ds_read_b64_tr_b16 v[146:147], v244 offset:1024
	ds_read_b64_tr_b16 v[148:149], v244 offset:3072
	s_waitcnt lgkmcnt(4)
	v_mfma_f32_32x32x16_bf16 v[98:113], v[138:141], v[202:205], v[98:113]
	ds_read_b64_tr_b16 v[150:151], v244 offset:5120
	ds_read_b64_tr_b16 v[152:153], v244 offset:7168
	s_waitcnt lgkmcnt(4)
	v_mfma_f32_32x32x16_bf16 v[98:113], v[142:145], v[206:209], v[98:113]
	ds_read_b64_tr_b16 v[154:155], v244 offset:9216
	ds_read_b64_tr_b16 v[156:157], v244 offset:11264
	s_waitcnt lgkmcnt(4)
	v_mfma_f32_32x32x16_bf16 v[82:97], v[130:133], v[146:149], v[82:97]
	ds_read_b64_tr_b16 v[158:159], v244 offset:13312
	ds_read_b64_tr_b16 v[160:161], v244 offset:15360
	s_waitcnt lgkmcnt(4)
	v_mfma_f32_32x32x16_bf16 v[82:97], v[134:137], v[150:153], v[82:97]
	ds_read_b64_tr_b16 v[194:195], v244 offset:1536
	ds_read_b64_tr_b16 v[196:197], v244 offset:3584
	s_waitcnt lgkmcnt(4)
	v_mfma_f32_32x32x16_bf16 v[82:97], v[138:141], v[154:157], v[82:97]
	ds_read_b64_tr_b16 v[198:199], v244 offset:5632
	ds_read_b64_tr_b16 v[200:201], v244 offset:7680
	s_waitcnt lgkmcnt(4)
	v_mfma_f32_32x32x16_bf16 v[82:97], v[142:145], v[158:161], v[82:97]
	ds_read_b64_tr_b16 v[202:203], v244 offset:9728
	ds_read_b64_tr_b16 v[204:205], v244 offset:11776
	s_waitcnt lgkmcnt(4)
	v_mfma_f32_32x32x16_bf16 v[66:81], v[130:133], v[194:197], v[66:81]
	ds_read_b64_tr_b16 v[206:207], v244 offset:13824
	ds_read_b64_tr_b16 v[208:209], v244 offset:15872
	s_waitcnt lgkmcnt(4)
	v_mfma_f32_32x32x16_bf16 v[66:81], v[134:137], v[198:201], v[66:81]
	ds_read_b64_tr_b16 v[146:147], v244 offset:16384
	ds_read_b64_tr_b16 v[148:149], v244 offset:18432
	s_waitcnt lgkmcnt(4)
	v_mfma_f32_32x32x16_bf16 v[66:81], v[138:141], v[202:205], v[66:81]
	ds_read_b64_tr_b16 v[150:151], v244 offset:20480
	ds_read_b64_tr_b16 v[152:153], v244 offset:22528
	s_waitcnt lgkmcnt(4)
	v_mfma_f32_32x32x16_bf16 v[66:81], v[142:145], v[206:209], v[66:81]
	ds_read_b64_tr_b16 v[154:155], v244 offset:24576
	ds_read_b64_tr_b16 v[156:157], v244 offset:26624
	s_waitcnt lgkmcnt(4)
	v_mfma_f32_32x32x16_bf16 v[50:65], v[130:133], v[146:149], v[50:65]
	ds_read_b64_tr_b16 v[158:159], v244 offset:28672
	ds_read_b64_tr_b16 v[160:161], v244 offset:30720
	s_waitcnt lgkmcnt(4)
	v_mfma_f32_32x32x16_bf16 v[50:65], v[134:137], v[150:153], v[50:65]
	ds_read_b64_tr_b16 v[194:195], v244 offset:16896
	ds_read_b64_tr_b16 v[196:197], v244 offset:18944
	s_waitcnt lgkmcnt(4)
	v_mfma_f32_32x32x16_bf16 v[50:65], v[138:141], v[154:157], v[50:65]
	ds_read_b64_tr_b16 v[198:199], v244 offset:20992
	ds_read_b64_tr_b16 v[200:201], v244 offset:23040
	s_waitcnt lgkmcnt(4)
	v_mfma_f32_32x32x16_bf16 v[50:65], v[142:145], v[158:161], v[50:65]
	ds_read_b64_tr_b16 v[202:203], v244 offset:25088
	ds_read_b64_tr_b16 v[204:205], v244 offset:27136
	s_waitcnt lgkmcnt(4)
	v_mfma_f32_32x32x16_bf16 v[34:49], v[130:133], v[194:197], v[34:49]
	ds_read_b64_tr_b16 v[206:207], v244 offset:29184
	ds_read_b64_tr_b16 v[208:209], v244 offset:31232
	s_waitcnt lgkmcnt(4)
	v_mfma_f32_32x32x16_bf16 v[34:49], v[134:137], v[198:201], v[34:49]
	ds_read_b64_tr_b16 v[146:147], v244 offset:17408
	ds_read_b64_tr_b16 v[148:149], v244 offset:19456
	s_waitcnt lgkmcnt(4)
	v_mfma_f32_32x32x16_bf16 v[34:49], v[138:141], v[202:205], v[34:49]
	ds_read_b64_tr_b16 v[150:151], v244 offset:21504
	ds_read_b64_tr_b16 v[152:153], v244 offset:23552
	s_waitcnt lgkmcnt(4)
	v_mfma_f32_32x32x16_bf16 v[34:49], v[142:145], v[206:209], v[34:49]
	ds_read_b64_tr_b16 v[154:155], v244 offset:25600
	ds_read_b64_tr_b16 v[156:157], v244 offset:27648
	s_waitcnt lgkmcnt(4)
	v_mfma_f32_32x32x16_bf16 v[18:33], v[130:133], v[146:149], v[18:33]
	ds_read_b64_tr_b16 v[158:159], v244 offset:29696
	ds_read_b64_tr_b16 v[160:161], v244 offset:31744
	s_waitcnt lgkmcnt(4)
	v_mfma_f32_32x32x16_bf16 v[18:33], v[134:137], v[150:153], v[18:33]
	ds_read_b64_tr_b16 v[194:195], v244 offset:17920
	ds_read_b64_tr_b16 v[196:197], v244 offset:19968
	s_waitcnt lgkmcnt(4)
	v_mfma_f32_32x32x16_bf16 v[18:33], v[138:141], v[154:157], v[18:33]
	ds_read_b64_tr_b16 v[198:199], v244 offset:22016
	ds_read_b64_tr_b16 v[200:201], v244 offset:24064
	s_waitcnt lgkmcnt(4)
	v_mfma_f32_32x32x16_bf16 v[18:33], v[142:145], v[158:161], v[18:33]
	ds_read_b64_tr_b16 v[202:203], v244 offset:26112
	ds_read_b64_tr_b16 v[204:205], v244 offset:28160
	s_waitcnt lgkmcnt(4)
	v_mfma_f32_32x32x16_bf16 v[2:17], v[130:133], v[194:197], v[2:17]
	ds_read_b64_tr_b16 v[206:207], v244 offset:30208
	ds_read_b64_tr_b16 v[208:209], v244 offset:32256
	s_waitcnt lgkmcnt(4)
	v_mfma_f32_32x32x16_bf16 v[2:17], v[134:137], v[198:201], v[2:17]
	s_waitcnt lgkmcnt(2)
	v_mfma_f32_32x32x16_bf16 v[2:17], v[138:141], v[202:205], v[2:17]
	s_waitcnt lgkmcnt(0)
	v_mfma_f32_32x32x16_bf16 v[2:17], v[142:145], v[206:209], v[2:17]
	s_waitcnt vmcnt(0)
	s_add_u32 s22, s22, 0x180000
	s_addc_u32 s23, s23, 0
	s_add_i32 s80, s80, 2
	s_and_b64 vcc, exec, s[24:25]
	s_waitcnt vmcnt(0) lgkmcnt(0)
	s_barrier
	s_cbranch_vccnz .LBB0_1445

; __device__ __forceinline__ void partialSM(f32x16& p0, f32x16& p1, float& m_reg, float& mn, float& alpha) {
;     ...
;   float mnC = -mn * C;
; #pragma unroll
;   for (int r = 0; r < 16; ++r) p0[r] = fmaf(p0[r], C, mnC);
; #pragma unroll
;   for (int r = 0; r < 16; ++r) p1[r] = fmaf(p1[r], C, mnC);
; #pragma unroll
;   for (int r = 0; r < 16; ++r) p0[r] = __builtin_amdgcn_exp2f(p0[r]);
; }
; __device__ __forceinline__ void finishSM(f32x16& p0, f32x16& p1, float alpha, float& l_reg, bf16x8& pa0, bf16x8& pa1, bf16x8& pa2, bf16x8& pa3) {
; #pragma unroll
;   for (int r = 0; r < 16; ++r) p1[r] = __builtin_amdgcn_exp2f(p1[r]);
;   float ps = 0;
; #pragma unroll
;   for (int r = 0; r < 16; ++r) ps += p0[r];
; #pragma unroll
;   for (int r = 0; r < 16; ++r) ps += p1[r];
;   { auto rr = __builtin_amdgcn_permlane32_swap(__float_as_uint(ps), __float_as_uint(ps), false, false);
;     ps = __uint_as_float(rr[0]) + __uint_as_float(rr[1]); }
;   l_reg = l_reg * alpha + ps;
;     ...
;   PK4(p0, 0, pa0); PK4(p0, 8, pa1); PK4(p1, 0, pa2); PK4(p1, 8, pa3);
;     ...
; }
; __device__ __forceinline__ void pv_all_rolling(f32x16* o, int vb, bf16x8 pa0, bf16x8 pa1, bf16x8 pa2, bf16x8 pa3) {
;   const bf16x8 pa[4] = {pa0, pa1, pa2, pa3}; s16x4 l[3], h[3];
;   asm volatile("s_waitcnt lgkmcnt(0)" ::: "memory");
;   pv_rd<0>(vb, l[0], h[0]); pv_rd<1>(vb, l[1], h[1]);
;   pv_step<0>(o, vb, pa, l, h);
.LBB0_1440:
	v_cndmask_b32_e64 v246, v247, v246, s[6:7]
	v_mul_f32_e32 v194, 0xbe0293ee, v246
	v_fmamk_f32 v146, v146, 0x3e0293ee, v194
	v_fmamk_f32 v147, v147, 0x3e0293ee, v194
	v_fmamk_f32 v148, v148, 0x3e0293ee, v194
	v_fmamk_f32 v149, v149, 0x3e0293ee, v194
	v_fmamk_f32 v150, v150, 0x3e0293ee, v194
	v_fmamk_f32 v151, v151, 0x3e0293ee, v194
	v_fmamk_f32 v152, v152, 0x3e0293ee, v194
	v_fmamk_f32 v153, v153, 0x3e0293ee, v194
	v_fmamk_f32 v154, v154, 0x3e0293ee, v194
	v_fmamk_f32 v155, v155, 0x3e0293ee, v194
	v_fmamk_f32 v156, v156, 0x3e0293ee, v194
	v_fmamk_f32 v157, v157, 0x3e0293ee, v194
	v_fmamk_f32 v158, v158, 0x3e0293ee, v194
	v_fmamk_f32 v159, v159, 0x3e0293ee, v194
	v_fmamk_f32 v160, v160, 0x3e0293ee, v194
	v_fmamk_f32 v161, v161, 0x3e0293ee, v194
	v_fmamk_f32 v130, v130, 0x3e0293ee, v194
	v_fmamk_f32 v131, v131, 0x3e0293ee, v194
	v_fmamk_f32 v132, v132, 0x3e0293ee, v194
	v_fmamk_f32 v133, v133, 0x3e0293ee, v194
	v_fmamk_f32 v134, v134, 0x3e0293ee, v194
	v_fmamk_f32 v135, v135, 0x3e0293ee, v194
	v_fmamk_f32 v136, v136, 0x3e0293ee, v194
	v_fmamk_f32 v137, v137, 0x3e0293ee, v194
	v_fmamk_f32 v138, v138, 0x3e0293ee, v194
	v_fmamk_f32 v139, v139, 0x3e0293ee, v194
	v_fmamk_f32 v140, v140, 0x3e0293ee, v194
	v_fmamk_f32 v141, v141, 0x3e0293ee, v194
	v_fmamk_f32 v142, v142, 0x3e0293ee, v194
	v_fmamk_f32 v143, v143, 0x3e0293ee, v194
	v_fmamk_f32 v144, v144, 0x3e0293ee, v194
	v_fmac_f32_e32 v194, 0x3e0293ee, v145
	v_exp_f32_e32 v145, v146
	v_exp_f32_e32 v146, v147
	v_exp_f32_e32 v147, v148
	v_exp_f32_e32 v148, v149
	v_exp_f32_e32 v149, v150
	v_exp_f32_e32 v150, v151
	v_exp_f32_e32 v151, v152
	v_exp_f32_e32 v152, v153
	v_exp_f32_e32 v153, v154
	v_exp_f32_e32 v154, v155
	v_exp_f32_e32 v155, v156
	v_exp_f32_e32 v156, v157
	v_exp_f32_e32 v157, v158
	v_exp_f32_e32 v158, v159
	v_exp_f32_e32 v159, v160
	v_exp_f32_e32 v160, v161
	v_exp_f32_e32 v161, v130
	v_add_f32_e32 v130, 0, v145
	v_add_f32_e32 v130, v146, v130
	v_add_f32_e32 v130, v147, v130
	v_add_f32_e32 v130, v148, v130
	v_add_f32_e32 v130, v149, v130
	v_add_f32_e32 v130, v150, v130
	v_add_f32_e32 v130, v151, v130
	s_waitcnt vmcnt(0)
	s_barrier
	s_setprio 0
	v_add_f32_e32 v130, v152, v130
	v_add_f32_e32 v130, v153, v130
	v_add_f32_e32 v130, v154, v130
	v_add_f32_e32 v130, v155, v130
	v_add_f32_e32 v130, v156, v130
	v_add_f32_e32 v130, v157, v130
	v_exp_f32_e32 v195, v131
	v_add_f32_e32 v130, v158, v130
	v_exp_f32_e32 v196, v132
	v_add_f32_e32 v130, v159, v130
	v_exp_f32_e32 v197, v133
	v_add_f32_e32 v130, v160, v130
	v_exp_f32_e32 v198, v134
	v_add_f32_e32 v130, v161, v130
	v_exp_f32_e32 v199, v135
	v_add_f32_e32 v130, v195, v130
	v_exp_f32_e32 v200, v136
	v_add_f32_e32 v130, v196, v130
	v_exp_f32_e32 v201, v137
	v_add_f32_e32 v130, v197, v130
	v_exp_f32_e32 v202, v138
	v_add_f32_e32 v130, v198, v130
	v_exp_f32_e32 v203, v139
	v_add_f32_e32 v130, v199, v130
	v_exp_f32_e32 v204, v140
	v_add_f32_e32 v130, v200, v130
	v_exp_f32_e32 v205, v141
	v_add_f32_e32 v130, v201, v130
	v_exp_f32_e32 v206, v142
	v_add_f32_e32 v130, v202, v130
	v_exp_f32_e32 v207, v143
	v_add_f32_e32 v130, v203, v130
	v_exp_f32_e32 v208, v144
	v_add_f32_e32 v130, v204, v130
	v_exp_f32_e32 v194, v194
	v_add_f32_e32 v130, v205, v130
	v_add_f32_e32 v130, v206, v130
	v_add_f32_e32 v130, v207, v130
	v_add_f32_e32 v130, v208, v130
	v_add_f32_e32 v247, v194, v130
	v_mov_b32_e32 v248, v247
	s_nop 1
	v_permlane32_swap_b32_e32 v247, v248
	v_cvt_pk_bf16_f32 v130, v145, v146
	v_cvt_pk_bf16_f32 v131, v147, v148
	v_cvt_pk_bf16_f32 v132, v149, v150
	v_cvt_pk_bf16_f32 v133, v151, v152
	v_cvt_pk_bf16_f32 v134, v153, v154
	v_cvt_pk_bf16_f32 v135, v155, v156
	v_cvt_pk_bf16_f32 v136, v157, v158
	v_cvt_pk_bf16_f32 v137, v159, v160
	v_cvt_pk_bf16_f32 v138, v161, v195
	v_cvt_pk_bf16_f32 v139, v196, v197
	v_cvt_pk_bf16_f32 v140, v198, v199
	v_cvt_pk_bf16_f32 v141, v200, v201
	v_cvt_pk_bf16_f32 v142, v202, v203
	v_cvt_pk_bf16_f32 v143, v204, v205
	v_cvt_pk_bf16_f32 v144, v206, v207
	v_cvt_pk_bf16_f32 v145, v208, v194
	s_nop 0
	v_permlane32_swap_b32_e32 v130, v132
	v_permlane32_swap_b32_e32 v131, v133
	v_permlane32_swap_b32_e32 v134, v136
	v_permlane32_swap_b32_e32 v135, v137
	v_permlane32_swap_b32_e32 v138, v140
	v_permlane32_swap_b32_e32 v139, v141
	v_permlane32_swap_b32_e32 v142, v144
	v_permlane32_swap_b32_e32 v143, v145
	s_waitcnt lgkmcnt(0)
	ds_read_b64_tr_b16 v[146:147], v213 offset:0
	ds_read_b64_tr_b16 v[148:149], v213 offset:2048
	ds_read_b64_tr_b16 v[150:151], v213 offset:4096
	ds_read_b64_tr_b16 v[152:153], v213 offset:6144
	ds_read_b64_tr_b16 v[154:155], v213 offset:8192
	ds_read_b64_tr_b16 v[156:157], v213 offset:10240
	v_lshl_add_u64 v[232:233], v[218:219], 0, s[22:23]
	v_lshl_add_u64 v[232:233], v[232:233], 0, s[10:11]
	s_add_i32 m0, s62, 0x8000
	s_nop 0
	global_load_lds_dwordx4 v[232:233], off
	s_waitcnt lgkmcnt(4)
	s_nop 0
	v_mfma_f32_32x32x16_bf16 v[114:129], v[130:133], v[146:149], v[114:129]
	ds_read_b64_tr_b16 v[158:159], v213 offset:12288
	ds_read_b64_tr_b16 v[160:161], v213 offset:14336
	v_lshl_add_u64 v[232:233], v[218:219], 0, s[22:23]
	v_lshl_add_u64 v[232:233], v[232:233], 0, s[12:13]
	s_add_i32 m0, s62, 0xc000
	s_nop 0
	global_load_lds_dwordx4 v[232:233], off
	s_waitcnt lgkmcnt(4)
	v_mfma_f32_32x32x16_bf16 v[114:129], v[134:137], v[150:153], v[114:129]
	ds_read_b64_tr_b16 v[194:195], v213 offset:512
	ds_read_b64_tr_b16 v[196:197], v213 offset:2560
	v_lshl_add_u64 v[232:233], v[220:221], 0, s[22:23]
	v_lshl_add_u64 v[232:233], v[232:233], 0, s[10:11]
	s_add_i32 m0, s62, 0x8400
	s_nop 0
	global_load_lds_dwordx4 v[232:233], off
	s_waitcnt lgkmcnt(4)
; #define SBAR() __builtin_amdgcn_sched_barrier(0)
; #define DPUB() do { asm volatile("s_waitcnt vmcnt(0)" ::: "memory"); __syncthreads(); } while (0)
; #define DTILE(b) do { f32x16 p0 = f32x16{}, p1 = f32x16{}; float mn, al; bf16x8 pa0, pa1, pa2, pa3; \
;     qkt_rolling<(b) * DA_KB>(p0, p1, ka0, qr); partialSM(p0, p1, m_reg, mn, al); DRESC(al); finishSM(p0, p1, al, l_reg, pa0, pa1, pa2, pa3); SBAR(); \
;     pv_all_rolling(o, vb0 + (b) * DA_VB, pa0, pa1, pa2, pa3); } while (0)
; template <int I> __device__ __forceinline__ void pv_step(f32x16* o, int vb, const bf16x8 (&pa)[4], s16x4 (&l)[3], s16x4 (&h)[3]) {
;   if constexpr (I + 2 < 32) pv_rd<(I + 2 < 32 ? I + 2 : 0)>(vb, l[(I + 2) % 3], h[(I + 2) % 3]);
;   if constexpr (I + 2 < 32) asm volatile("s_waitcnt lgkmcnt(4)" ::: "memory"); else if constexpr (I + 1 < 32) asm volatile("s_waitcnt lgkmcnt(2)" ::: "memory"); else asm volatile("s_waitcnt lgkmcnt(0)" ::: "memory");
;   SBAR();
;   const s16x4 L = l[I % 3], H = h[I % 3];
;   o[I >> 2] = __builtin_amdgcn_mfma_f32_32x32x16_bf16(pa[I & 3], (bf16x8){L[0], L[1], L[2], L[3], H[0], H[1], H[2], H[3]}, o[I >> 2], 0, 0, 0);
;   SBAR();
;   if constexpr (I + 1 < 32) pv_step<(I + 1 < 32 ? I + 1 : 31)>(o, vb, pa, l, h);
; }
; __device__ __forceinline__ void unit_body_da(const Unit& U, char* lds) {
;     ...
;   for (int j = 0; j < NT; j += 2) {
;     DDMA(j + 1, 1); SBAR();
;     DTILE(0); SBAR(); DPUB();
;     if (j + 2 < NT) DDMA(j + 2, 0); SBAR();
;     DTILE(1); SBAR(); DPUB();
	v_mfma_f32_32x32x16_bf16 v[114:129], v[138:141], v[154:157], v[114:129]
	ds_read_b64_tr_b16 v[198:199], v213 offset:4608
	ds_read_b64_tr_b16 v[200:201], v213 offset:6656
	v_lshl_add_u64 v[232:233], v[220:221], 0, s[22:23]
	v_lshl_add_u64 v[232:233], v[232:233], 0, s[12:13]
	s_add_i32 m0, s62, 0xc400
	s_nop 0
	global_load_lds_dwordx4 v[232:233], off
	s_waitcnt lgkmcnt(4)
	v_mfma_f32_32x32x16_bf16 v[114:129], v[142:145], v[158:161], v[114:129]
	ds_read_b64_tr_b16 v[202:203], v213 offset:8704
	ds_read_b64_tr_b16 v[204:205], v213 offset:10752
	s_waitcnt lgkmcnt(4)
	v_mfma_f32_32x32x16_bf16 v[98:113], v[130:133], v[194:197], v[98:113]
	ds_read_b64_tr_b16 v[206:207], v213 offset:12800
	ds_read_b64_tr_b16 v[208:209], v213 offset:14848
	s_waitcnt lgkmcnt(4)
	v_mfma_f32_32x32x16_bf16 v[98:113], v[134:137], v[198:201], v[98:113]
	ds_read_b64_tr_b16 v[146:147], v213 offset:1024
	ds_read_b64_tr_b16 v[148:149], v213 offset:3072
	s_waitcnt lgkmcnt(4)
	v_mfma_f32_32x32x16_bf16 v[98:113], v[138:141], v[202:205], v[98:113]
	ds_read_b64_tr_b16 v[150:151], v213 offset:5120
	ds_read_b64_tr_b16 v[152:153], v213 offset:7168
	s_waitcnt lgkmcnt(4)
	v_mfma_f32_32x32x16_bf16 v[98:113], v[142:145], v[206:209], v[98:113]
	ds_read_b64_tr_b16 v[154:155], v213 offset:9216
	ds_read_b64_tr_b16 v[156:157], v213 offset:11264
	s_waitcnt lgkmcnt(4)
	v_mfma_f32_32x32x16_bf16 v[82:97], v[130:133], v[146:149], v[82:97]
	ds_read_b64_tr_b16 v[158:159], v213 offset:13312
	ds_read_b64_tr_b16 v[160:161], v213 offset:15360
	s_waitcnt lgkmcnt(4)
	v_mfma_f32_32x32x16_bf16 v[82:97], v[134:137], v[150:153], v[82:97]
	ds_read_b64_tr_b16 v[194:195], v213 offset:1536
	ds_read_b64_tr_b16 v[196:197], v213 offset:3584
	s_waitcnt lgkmcnt(4)
	v_mfma_f32_32x32x16_bf16 v[82:97], v[138:141], v[154:157], v[82:97]
	ds_read_b64_tr_b16 v[198:199], v213 offset:5632
	ds_read_b64_tr_b16 v[200:201], v213 offset:7680
	s_waitcnt lgkmcnt(4)
	v_mfma_f32_32x32x16_bf16 v[82:97], v[142:145], v[158:161], v[82:97]
	ds_read_b64_tr_b16 v[202:203], v213 offset:9728
	ds_read_b64_tr_b16 v[204:205], v213 offset:11776
	s_waitcnt lgkmcnt(4)
	v_mfma_f32_32x32x16_bf16 v[66:81], v[130:133], v[194:197], v[66:81]
	ds_read_b64_tr_b16 v[206:207], v213 offset:13824
	ds_read_b64_tr_b16 v[208:209], v213 offset:15872
	s_waitcnt lgkmcnt(4)
	v_mfma_f32_32x32x16_bf16 v[66:81], v[134:137], v[198:201], v[66:81]
	ds_read_b64_tr_b16 v[146:147], v213 offset:16384
	ds_read_b64_tr_b16 v[148:149], v213 offset:18432
	s_waitcnt lgkmcnt(4)
	v_mfma_f32_32x32x16_bf16 v[66:81], v[138:141], v[202:205], v[66:81]
	ds_read_b64_tr_b16 v[150:151], v213 offset:20480
	ds_read_b64_tr_b16 v[152:153], v213 offset:22528
	s_waitcnt lgkmcnt(4)
	v_mfma_f32_32x32x16_bf16 v[66:81], v[142:145], v[206:209], v[66:81]
	ds_read_b64_tr_b16 v[154:155], v213 offset:24576
	ds_read_b64_tr_b16 v[156:157], v213 offset:26624
	s_waitcnt lgkmcnt(4)
	v_mfma_f32_32x32x16_bf16 v[50:65], v[130:133], v[146:149], v[50:65]
	ds_read_b64_tr_b16 v[158:159], v213 offset:28672
	ds_read_b64_tr_b16 v[160:161], v213 offset:30720
	s_waitcnt lgkmcnt(4)
	v_mfma_f32_32x32x16_bf16 v[50:65], v[134:137], v[150:153], v[50:65]
	ds_read_b64_tr_b16 v[194:195], v213 offset:16896
	ds_read_b64_tr_b16 v[196:197], v213 offset:18944
	s_waitcnt lgkmcnt(4)
	v_mfma_f32_32x32x16_bf16 v[50:65], v[138:141], v[154:157], v[50:65]
	ds_read_b64_tr_b16 v[198:199], v213 offset:20992
	ds_read_b64_tr_b16 v[200:201], v213 offset:23040
	s_waitcnt lgkmcnt(4)
	v_mfma_f32_32x32x16_bf16 v[50:65], v[142:145], v[158:161], v[50:65]
	ds_read_b64_tr_b16 v[202:203], v213 offset:25088
	ds_read_b64_tr_b16 v[204:205], v213 offset:27136
	s_waitcnt lgkmcnt(4)
	v_mfma_f32_32x32x16_bf16 v[34:49], v[130:133], v[194:197], v[34:49]
	ds_read_b64_tr_b16 v[206:207], v213 offset:29184
	ds_read_b64_tr_b16 v[208:209], v213 offset:31232
	s_waitcnt lgkmcnt(4)
	v_mfma_f32_32x32x16_bf16 v[34:49], v[134:137], v[198:201], v[34:49]
	ds_read_b64_tr_b16 v[146:147], v213 offset:17408
	ds_read_b64_tr_b16 v[148:149], v213 offset:19456
	s_waitcnt lgkmcnt(4)
	v_mfma_f32_32x32x16_bf16 v[34:49], v[138:141], v[202:205], v[34:49]
	ds_read_b64_tr_b16 v[150:151], v213 offset:21504
	ds_read_b64_tr_b16 v[152:153], v213 offset:23552
	s_waitcnt lgkmcnt(4)
	v_mfma_f32_32x32x16_bf16 v[34:49], v[142:145], v[206:209], v[34:49]
	ds_read_b64_tr_b16 v[154:155], v213 offset:25600
	ds_read_b64_tr_b16 v[156:157], v213 offset:27648
	s_waitcnt lgkmcnt(4)
	v_mfma_f32_32x32x16_bf16 v[18:33], v[130:133], v[146:149], v[18:33]
	ds_read_b64_tr_b16 v[158:159], v213 offset:29696
	ds_read_b64_tr_b16 v[160:161], v213 offset:31744
	s_waitcnt lgkmcnt(4)
	v_mfma_f32_32x32x16_bf16 v[18:33], v[134:137], v[150:153], v[18:33]
	ds_read_b64_tr_b16 v[194:195], v213 offset:17920
	ds_read_b64_tr_b16 v[196:197], v213 offset:19968
	s_waitcnt lgkmcnt(4)
	v_mfma_f32_32x32x16_bf16 v[18:33], v[138:141], v[154:157], v[18:33]
	ds_read_b64_tr_b16 v[198:199], v213 offset:22016
	ds_read_b64_tr_b16 v[200:201], v213 offset:24064
	s_waitcnt lgkmcnt(4)
	v_mfma_f32_32x32x16_bf16 v[18:33], v[142:145], v[158:161], v[18:33]
	ds_read_b64_tr_b16 v[202:203], v213 offset:26112
	ds_read_b64_tr_b16 v[204:205], v213 offset:28160
	s_waitcnt lgkmcnt(4)
	v_mfma_f32_32x32x16_bf16 v[2:17], v[130:133], v[194:197], v[2:17]
	ds_read_b64_tr_b16 v[206:207], v213 offset:30208
	ds_read_b64_tr_b16 v[208:209], v213 offset:32256
	s_waitcnt lgkmcnt(4)
	v_mfma_f32_32x32x16_bf16 v[2:17], v[134:137], v[198:201], v[2:17]
	s_waitcnt lgkmcnt(2)
	v_mfma_f32_32x32x16_bf16 v[2:17], v[138:141], v[202:205], v[2:17]
	s_waitcnt lgkmcnt(0)
	v_mfma_f32_32x32x16_bf16 v[2:17], v[142:145], v[206:209], v[2:17]
	s_waitcnt vmcnt(0)
	s_cmp_ge_u32 s80, s96
	s_cselect_b64 s[24:25], -1, 0
	s_and_b64 vcc, exec, s[24:25]
	s_waitcnt vmcnt(0) lgkmcnt(0)
	s_barrier
